# attention softmax trims: max tree 10->8, sub via v_pk_add (17->11), row-sum via pk_add tree (17->10)
# baseline (speedup 1.0000x reference)
.LBB0_375:
	s_or_b64 exec, exec, s[14:15]
	s_add_i32 s14, s17, 1
	s_ashr_i32 s3, s2, 31
	s_bitcmp1_b32 s17, 0
	v_lshl_add_u64 v[2:3], s[2:3], 1, v[130:131]
	s_cselect_b32 s2, 0x2e00, 0
	s_add_i32 s2, s18, s2
	v_add3_u32 v0, s2, v153, v154
	global_load_dwordx4 v[94:97], v[2:3], off
	ds_read_b128 v[132:135], v0
	ds_read_b128 v[136:139], v0 offset:32
	ds_read_b128 v[140:143], v0 offset:64
	ds_read_b128 v[160:163], v0 offset:96
	ds_read_b128 v[164:167], v0 offset:128
	ds_read_b128 v[168:171], v0 offset:160
	v_add3_u32 v0, s2, v102, v155
	v_add_u32_e32 v2, 0x1800, v0
	v_add_u32_e32 v0, 0x2000, v0
	ds_read2_b64 v[172:175], v2 offset0:64 offset1:66
	ds_read2_b64 v[176:179], v2 offset0:68 offset1:70
	ds_read2_b64 v[180:183], v0 offset0:128 offset1:130
	ds_read2_b64 v[184:187], v0 offset0:132 offset1:134
	s_bitcmp1_b32 s14, 0
	s_cselect_b32 s2, 0x2e00, 0
	s_waitcnt lgkmcnt(9)
	v_mfma_f32_32x32x16_bf16 v[48:63], v[132:135], v[70:73], 0
	s_add_i32 s15, s18, s2
	s_waitcnt lgkmcnt(8)
	v_mfma_f32_32x32x16_bf16 v[48:63], v[136:139], v[74:77], v[48:63]
	s_waitcnt lgkmcnt(7)
	v_mfma_f32_32x32x16_bf16 v[48:63], v[140:143], v[78:81], v[48:63]
	s_waitcnt lgkmcnt(6)
	v_mfma_f32_32x32x16_bf16 v[48:63], v[160:163], v[82:85], v[48:63]
	s_waitcnt lgkmcnt(5)
	v_mfma_f32_32x32x16_bf16 v[48:63], v[164:167], v[86:89], v[48:63]
	s_waitcnt lgkmcnt(4)
	v_mfma_f32_32x32x16_bf16 v[48:63], v[168:171], v[90:93], v[48:63]
	s_nop 11
	v_max3_f32 v0, v48, v49, v50
	v_max3_f32 v0, v0, v51, v52
	v_max3_f32 v0, v0, v53, v54
	v_max3_f32 v0, v0, v55, v56
	v_max3_f32 v0, v0, v57, v58
	v_max3_f32 v0, v0, v59, v60
	v_max3_f32 v0, v0, v61, v62
	v_max_f32_e32 v0, v0, v63
	ds_bpermute_b32 v2, v103, v0
	s_waitcnt lgkmcnt(0)
	v_max3_f32 v115, v117, v0, v2
	v_sub_f32_e32 v0, v117, v115
	v_mov_b32_e32 v188, v115
	v_mov_b32_e32 v189, v115
	v_pk_add_f32 v[2:3], v[48:49], v[188:189] neg_lo:[0,1] neg_hi:[0,1]
	v_pk_add_f32 v[4:5], v[50:51], v[188:189] neg_lo:[0,1] neg_hi:[0,1]
	v_pk_add_f32 v[6:7], v[52:53], v[188:189] neg_lo:[0,1] neg_hi:[0,1]
	v_pk_add_f32 v[8:9], v[54:55], v[188:189] neg_lo:[0,1] neg_hi:[0,1]
	v_exp_f32_e32 v2, v2
	v_exp_f32_e32 v3, v3
	v_exp_f32_e32 v4, v4
	v_exp_f32_e32 v5, v5
	v_exp_f32_e32 v6, v6
	v_exp_f32_e32 v7, v7
	v_exp_f32_e32 v8, v8
	v_exp_f32_e32 v9, v9
	v_exp_f32_e32 v0, v0
	v_cvt_pk_bf16_f32 v48, v2, v3
	v_cvt_pk_bf16_f32 v49, v4, v5
	v_cvt_pk_bf16_f32 v50, v6, v7
	v_pk_mul_f32 v[46:47], v[46:47], v[0:1] op_sel_hi:[1,0]
	v_pk_mul_f32 v[44:45], v[44:45], v[0:1] op_sel_hi:[1,0]
	v_pk_mul_f32 v[42:43], v[42:43], v[0:1] op_sel_hi:[1,0]
	v_pk_mul_f32 v[40:41], v[40:41], v[0:1] op_sel_hi:[1,0]
	v_pk_mul_f32 v[38:39], v[38:39], v[0:1] op_sel_hi:[1,0]
	v_pk_mul_f32 v[36:37], v[36:37], v[0:1] op_sel_hi:[1,0]
	v_pk_mul_f32 v[34:35], v[34:35], v[0:1] op_sel_hi:[1,0]
	v_pk_mul_f32 v[32:33], v[32:33], v[0:1] op_sel_hi:[1,0]
	v_pk_mul_f32 v[30:31], v[30:31], v[0:1] op_sel_hi:[1,0]
	v_cvt_pk_bf16_f32 v51, v8, v9
	v_pk_mul_f32 v[28:29], v[28:29], v[0:1] op_sel_hi:[1,0]
	v_pk_mul_f32 v[26:27], v[26:27], v[0:1] op_sel_hi:[1,0]
	v_pk_mul_f32 v[24:25], v[24:25], v[0:1] op_sel_hi:[1,0]
	v_pk_mul_f32 v[22:23], v[22:23], v[0:1] op_sel_hi:[1,0]
	v_pk_mul_f32 v[20:21], v[20:21], v[0:1] op_sel_hi:[1,0]
	v_pk_mul_f32 v[18:19], v[18:19], v[0:1] op_sel_hi:[1,0]
	v_pk_mul_f32 v[16:17], v[16:17], v[0:1] op_sel_hi:[1,0]
	v_mfma_f32_32x32x16_bf16 v[32:47], v[172:175], v[48:51], v[32:47]
	v_pk_add_f32 v[10:11], v[56:57], v[188:189] neg_lo:[0,1] neg_hi:[0,1]
	v_pk_add_f32 v[12:13], v[58:59], v[188:189] neg_lo:[0,1] neg_hi:[0,1]
	v_pk_add_f32 v[14:15], v[60:61], v[188:189] neg_lo:[0,1] neg_hi:[0,1]
	v_pk_add_f32 v[190:191], v[62:63], v[188:189] neg_lo:[0,1] neg_hi:[0,1]
	v_mfma_f32_32x32x16_bf16 v[16:31], v[180:183], v[48:51], v[16:31]
	v_exp_f32_e32 v10, v10
	v_exp_f32_e32 v11, v11
	v_exp_f32_e32 v12, v12
	v_exp_f32_e32 v13, v13
	v_exp_f32_e32 v14, v14
	v_exp_f32_e32 v15, v15
	v_exp_f32_e32 v48, v190
	v_exp_f32_e32 v49, v191
	v_cvt_pk_bf16_f32 v50, v10, v11
	v_cvt_pk_bf16_f32 v51, v12, v13
	v_cvt_pk_bf16_f32 v52, v14, v15
	v_cvt_pk_bf16_f32 v53, v48, v49
	s_nop 1
	v_mfma_f32_32x32x16_bf16 v[32:47], v[176:179], v[50:53], v[32:47]
	v_mfma_f32_32x32x16_bf16 v[16:31], v[184:187], v[50:53], v[16:31]
	v_add3_u32 v50, s15, v148, v149
	s_waitcnt vmcnt(1)
	ds_write_b128 v50, v[98:101]
	s_and_saveexec_b64 s[2:3], s[0:1]
	v_add3_u32 v50, s15, v150, v156
	ds_write_b128 v50, v[66:69]
	s_or_b64 exec, exec, s[2:3]
	v_pk_add_f32 v[2:3], v[2:3], v[4:5]
	v_pk_add_f32 v[6:7], v[6:7], v[8:9]
	v_pk_add_f32 v[10:11], v[10:11], v[12:13]
	v_pk_add_f32 v[14:15], v[14:15], v[48:49]
	v_pk_add_f32 v[2:3], v[2:3], v[6:7]
	v_pk_add_f32 v[10:11], v[10:11], v[14:15]
	s_nop 0
	v_pk_add_f32 v[2:3], v[2:3], v[10:11]
	s_nop 0
	v_add_f32_e32 v98, v2, v3
	s_add_i32 s16, s16, 32
	v_fmac_f32_e32 v98, v113, v0
	v_add3_u32 v0, s15, v151, v152
	s_cmp_eq_u32 s14, 39
	s_waitcnt vmcnt(0)
	ds_write_b128 v0, v[94:97] offset:6656
	s_waitcnt lgkmcnt(0)
	s_barrier
	s_cbranch_scc1 .LBB0_379
	v_mov_b32_e32 v113, v98
	v_mov_b32_e32 v117, v115
	s_mov_b32 s17, s14
	s_branch .LBB0_373

.LBB0_391:
	s_or_b64 exec, exec, s[2:3]
	s_bitcmp1_b32 s7, 0
	s_cselect_b32 s3, 0, 0x2e00
	s_cselect_b32 s2, 0x2e00, 0
	s_add_i32 s3, s18, s3
	v_add3_u32 v0, s3, v153, v154
	global_load_dwordx4 v[92:95], v[126:127], off
	ds_read_b128 v[128:131], v0
	ds_read_b128 v[132:135], v0 offset:32
	ds_read_b128 v[136:139], v0 offset:64
	ds_read_b128 v[160:163], v0 offset:96
	ds_read_b128 v[164:167], v0 offset:128
	ds_read_b128 v[168:171], v0 offset:160
	v_add3_u32 v0, s3, v102, v155
	v_add_u32_e32 v2, 0x1800, v0
	v_add_u32_e32 v0, 0x2000, v0
	ds_read2_b64 v[172:175], v2 offset0:64 offset1:66
	ds_read2_b64 v[176:179], v2 offset0:68 offset1:70
	ds_read2_b64 v[180:183], v0 offset0:128 offset1:130
	ds_read2_b64 v[184:187], v0 offset0:132 offset1:134
	s_add_i32 s8, s18, s2
	s_waitcnt lgkmcnt(9)
	v_mfma_f32_32x32x16_bf16 v[48:63], v[128:131], v[68:71], 0
	s_waitcnt lgkmcnt(8)
	v_mfma_f32_32x32x16_bf16 v[48:63], v[132:135], v[72:75], v[48:63]
	s_waitcnt lgkmcnt(7)
	v_mfma_f32_32x32x16_bf16 v[48:63], v[136:139], v[76:79], v[48:63]
	s_waitcnt lgkmcnt(6)
	v_mfma_f32_32x32x16_bf16 v[48:63], v[160:163], v[80:83], v[48:63]
	s_waitcnt lgkmcnt(5)
	v_mfma_f32_32x32x16_bf16 v[48:63], v[164:167], v[84:87], v[48:63]
	s_waitcnt lgkmcnt(4)
	v_mfma_f32_32x32x16_bf16 v[48:63], v[168:171], v[88:91], v[48:63]
	s_nop 11
	v_max3_f32 v0, v48, v49, v50
	v_max3_f32 v0, v0, v51, v52
	v_max3_f32 v0, v0, v53, v54
	v_max3_f32 v0, v0, v55, v56
	v_max3_f32 v0, v0, v57, v58
	v_max3_f32 v0, v0, v59, v60
	v_max3_f32 v0, v0, v61, v62
	v_max_f32_e32 v0, v0, v63
	ds_bpermute_b32 v2, v103, v0
	s_waitcnt lgkmcnt(0)
	v_max3_f32 v119, v121, v0, v2
	v_sub_f32_e32 v0, v121, v119
	v_mov_b32_e32 v188, v119
	v_mov_b32_e32 v189, v119
	v_pk_add_f32 v[2:3], v[48:49], v[188:189] neg_lo:[0,1] neg_hi:[0,1]
	v_pk_add_f32 v[4:5], v[50:51], v[188:189] neg_lo:[0,1] neg_hi:[0,1]
	v_pk_add_f32 v[6:7], v[52:53], v[188:189] neg_lo:[0,1] neg_hi:[0,1]
	v_pk_add_f32 v[8:9], v[54:55], v[188:189] neg_lo:[0,1] neg_hi:[0,1]
	v_exp_f32_e32 v2, v2
	v_exp_f32_e32 v3, v3
	v_exp_f32_e32 v4, v4
	v_exp_f32_e32 v5, v5
	v_exp_f32_e32 v6, v6
	v_exp_f32_e32 v7, v7
	v_exp_f32_e32 v8, v8
	v_exp_f32_e32 v9, v9
	v_exp_f32_e32 v0, v0
	v_cvt_pk_bf16_f32 v48, v2, v3
	v_cvt_pk_bf16_f32 v49, v4, v5
	v_cvt_pk_bf16_f32 v50, v6, v7
	v_pk_mul_f32 v[46:47], v[46:47], v[0:1] op_sel_hi:[1,0]
	v_pk_mul_f32 v[44:45], v[44:45], v[0:1] op_sel_hi:[1,0]
	v_pk_mul_f32 v[42:43], v[42:43], v[0:1] op_sel_hi:[1,0]
	v_pk_mul_f32 v[40:41], v[40:41], v[0:1] op_sel_hi:[1,0]
	v_pk_mul_f32 v[38:39], v[38:39], v[0:1] op_sel_hi:[1,0]
	v_pk_mul_f32 v[36:37], v[36:37], v[0:1] op_sel_hi:[1,0]
	v_pk_mul_f32 v[34:35], v[34:35], v[0:1] op_sel_hi:[1,0]
	v_pk_mul_f32 v[32:33], v[32:33], v[0:1] op_sel_hi:[1,0]
	v_pk_mul_f32 v[30:31], v[30:31], v[0:1] op_sel_hi:[1,0]
	v_cvt_pk_bf16_f32 v51, v8, v9
	v_pk_mul_f32 v[28:29], v[28:29], v[0:1] op_sel_hi:[1,0]
	v_pk_mul_f32 v[26:27], v[26:27], v[0:1] op_sel_hi:[1,0]
	v_pk_mul_f32 v[24:25], v[24:25], v[0:1] op_sel_hi:[1,0]
	v_pk_mul_f32 v[22:23], v[22:23], v[0:1] op_sel_hi:[1,0]
	v_pk_mul_f32 v[20:21], v[20:21], v[0:1] op_sel_hi:[1,0]
	v_pk_mul_f32 v[18:19], v[18:19], v[0:1] op_sel_hi:[1,0]
	v_pk_mul_f32 v[16:17], v[16:17], v[0:1] op_sel_hi:[1,0]
	v_mfma_f32_32x32x16_bf16 v[32:47], v[172:175], v[48:51], v[32:47]
	v_pk_add_f32 v[10:11], v[56:57], v[188:189] neg_lo:[0,1] neg_hi:[0,1]
	v_pk_add_f32 v[12:13], v[58:59], v[188:189] neg_lo:[0,1] neg_hi:[0,1]
	v_pk_add_f32 v[14:15], v[60:61], v[188:189] neg_lo:[0,1] neg_hi:[0,1]
	v_pk_add_f32 v[190:191], v[62:63], v[188:189] neg_lo:[0,1] neg_hi:[0,1]
	v_mfma_f32_32x32x16_bf16 v[16:31], v[180:183], v[48:51], v[16:31]
	v_exp_f32_e32 v10, v10
	v_exp_f32_e32 v11, v11
	v_exp_f32_e32 v12, v12
	v_exp_f32_e32 v13, v13
	v_exp_f32_e32 v14, v14
	v_exp_f32_e32 v15, v15
	v_exp_f32_e32 v48, v190
	v_exp_f32_e32 v49, v191
	v_cvt_pk_bf16_f32 v50, v10, v11
	v_cvt_pk_bf16_f32 v51, v12, v13
	v_cvt_pk_bf16_f32 v52, v14, v15
	v_cvt_pk_bf16_f32 v53, v48, v49
	s_nop 1
	v_mfma_f32_32x32x16_bf16 v[32:47], v[176:179], v[50:53], v[32:47]
	v_mfma_f32_32x32x16_bf16 v[16:31], v[184:187], v[50:53], v[16:31]
	v_add3_u32 v50, s8, v148, v149
	s_waitcnt vmcnt(1)
	ds_write_b128 v50, v[96:99]
	s_and_saveexec_b64 s[2:3], s[0:1]
	v_add3_u32 v50, s8, v150, v156
	ds_write_b128 v50, v[64:67]
	s_or_b64 exec, exec, s[2:3]
	v_pk_add_f32 v[2:3], v[2:3], v[4:5]
	v_pk_add_f32 v[6:7], v[6:7], v[8:9]
	v_pk_add_f32 v[10:11], v[10:11], v[12:13]
	v_pk_add_f32 v[14:15], v[14:15], v[48:49]
	v_pk_add_f32 v[2:3], v[2:3], v[6:7]
	v_pk_add_f32 v[10:11], v[10:11], v[14:15]
	s_nop 0
	v_pk_add_f32 v[2:3], v[2:3], v[10:11]
	s_nop 0
	v_add_f32_e32 v96, v2, v3
	s_add_i32 s7, s7, 1
	v_fmac_f32_e32 v96, v117, v0
	v_add3_u32 v0, s8, v151, v152
	v_add_u32_e32 v113, 32, v113
	v_lshl_add_u64 v[126:127], v[126:127], 0, 64
	s_cmp_eq_u32 s7, 8
	v_add_u32_e32 v115, 32, v115
	s_waitcnt vmcnt(0)
	ds_write_b128 v0, v[92:95] offset:6656
	s_waitcnt lgkmcnt(0)
	s_barrier
	s_cbranch_scc0 .LBB0_389
	v_add3_u32 v0, s8, v153, v154
	ds_read_b128 v[122:125], v0
	ds_read_b128 v[126:129], v0 offset:32
	ds_read_b128 v[130:133], v0 offset:64
	ds_read_b128 v[134:137], v0 offset:96
	ds_read_b128 v[138:141], v0 offset:128
	ds_read_b128 v[160:163], v0 offset:160
	v_add3_u32 v0, s8, v102, v155
	v_add_u32_e32 v2, 0x1800, v0
	v_add_u32_e32 v0, 0x2000, v0
	v_mov_b32_e32 v14, v1
	v_mov_b32_e32 v15, v1
	ds_read2_b64 v[164:167], v2 offset0:64 offset1:66
	ds_read2_b64 v[64:67], v2 offset0:68 offset1:70
	ds_read2_b64 v[168:171], v0 offset0:128 offset1:130
	ds_read2_b64 v[92:95], v0 offset0:132 offset1:134
	v_mov_b32_e32 v0, v1
	v_mov_b32_e32 v2, v1
	v_mov_b32_e32 v3, v1
	v_mov_b32_e32 v4, v1
	v_mov_b32_e32 v5, v1
	v_mov_b32_e32 v6, v1
	v_mov_b32_e32 v7, v1
	v_mov_b32_e32 v8, v1
	v_mov_b32_e32 v9, v1
	v_mov_b32_e32 v10, v1
	v_mov_b32_e32 v11, v1
	v_mov_b32_e32 v12, v1
	v_mov_b32_e32 v13, v1
	v_mov_b64_e32 v[62:63], v[14:15]
	v_mov_b64_e32 v[60:61], v[12:13]
	v_mov_b64_e32 v[58:59], v[10:11]
	v_mov_b64_e32 v[56:57], v[8:9]
	v_mov_b64_e32 v[54:55], v[6:7]
	v_mov_b64_e32 v[52:53], v[4:5]
	v_mov_b64_e32 v[50:51], v[2:3]
	v_mov_b64_e32 v[48:49], v[0:1]
	s_ashr_i32 s7, s6, 31
	v_mov_b32_e32 v121, v1
	s_waitcnt lgkmcnt(9)
	v_mfma_f32_32x32x16_bf16 v[48:63], v[122:125], v[68:71], v[48:63]
	s_waitcnt lgkmcnt(0)
	s_barrier
	s_add_i32 s5, s5, s26
	v_mfma_f32_32x32x16_bf16 v[48:63], v[126:129], v[72:75], v[48:63]
	v_mfma_f32_32x32x16_bf16 v[48:63], v[130:133], v[76:79], v[48:63]
	v_mfma_f32_32x32x16_bf16 v[48:63], v[134:137], v[80:83], v[48:63]
	v_mfma_f32_32x32x16_bf16 v[48:63], v[138:141], v[84:87], v[48:63]
	v_mfma_f32_32x32x16_bf16 v[48:63], v[160:163], v[88:91], v[48:63]
	s_nop 11
	v_max_f32_e32 v0, v49, v49
	v_max_f32_e32 v2, v48, v48
	v_max_f32_e32 v0, v2, v0
	v_max3_f32 v0, v0, v50, v51
	v_max3_f32 v0, v0, v52, v53
	v_max3_f32 v0, v0, v54, v55
	v_max3_f32 v0, v0, v56, v57
	v_max3_f32 v0, v0, v58, v59
	v_max3_f32 v0, v0, v60, v61
	v_max3_f32 v0, v0, v62, v63
	ds_bpermute_b32 v2, v103, v0
	s_waitcnt lgkmcnt(0)
	v_max3_f32 v6, v119, v0, v2
	v_sub_f32_e32 v2, v48, v6
	v_sub_f32_e32 v3, v49, v6
	v_exp_f32_e32 v2, v2
	v_sub_f32_e32 v4, v50, v6
	v_exp_f32_e32 v3, v3
	v_sub_f32_e32 v5, v51, v6
	v_exp_f32_e32 v4, v4
	v_sub_f32_e32 v7, v52, v6
	v_exp_f32_e32 v5, v5
	v_sub_f32_e32 v8, v53, v6
	v_exp_f32_e32 v7, v7
	v_add_f32_e32 v49, 0, v2
	v_sub_f32_e32 v9, v54, v6
	v_exp_f32_e32 v8, v8
	v_add_f32_e32 v49, v3, v49
	v_sub_f32_e32 v10, v55, v6
	v_exp_f32_e32 v9, v9
	v_add_f32_e32 v49, v4, v49
	v_sub_f32_e32 v0, v119, v6
	v_sub_f32_e32 v11, v56, v6
	v_exp_f32_e32 v10, v10
	v_add_f32_e32 v49, v5, v49
	v_sub_f32_e32 v12, v57, v6
	v_exp_f32_e32 v11, v11
	v_add_f32_e32 v49, v7, v49
	v_exp_f32_e32 v0, v0
	v_sub_f32_e32 v13, v58, v6
	v_exp_f32_e32 v12, v12
	v_add_f32_e32 v49, v8, v49
	v_sub_f32_e32 v14, v59, v6
	v_exp_f32_e32 v13, v13
	v_add_f32_e32 v49, v9, v49
	v_sub_f32_e32 v15, v60, v6
	v_exp_f32_e32 v14, v14
	v_add_f32_e32 v49, v10, v49
	v_sub_f32_e32 v48, v61, v6
	v_exp_f32_e32 v15, v15
	v_add_f32_e32 v49, v11, v49
	v_pk_mul_f32 v[46:47], v[46:47], v[0:1] op_sel_hi:[1,0]
	v_pk_mul_f32 v[44:45], v[44:45], v[0:1] op_sel_hi:[1,0]
	v_pk_mul_f32 v[42:43], v[42:43], v[0:1] op_sel_hi:[1,0]
	v_pk_mul_f32 v[40:41], v[40:41], v[0:1] op_sel_hi:[1,0]
	v_pk_mul_f32 v[38:39], v[38:39], v[0:1] op_sel_hi:[1,0]
	v_pk_mul_f32 v[36:37], v[36:37], v[0:1] op_sel_hi:[1,0]
	v_pk_mul_f32 v[34:35], v[34:35], v[0:1] op_sel_hi:[1,0]
	v_pk_mul_f32 v[32:33], v[32:33], v[0:1] op_sel_hi:[1,0]
	v_pk_mul_f32 v[30:31], v[30:31], v[0:1] op_sel_hi:[1,0]
	v_cvt_pk_bf16_f32 v2, v2, v3
	v_cvt_pk_bf16_f32 v3, v4, v5
	v_cvt_pk_bf16_f32 v4, v7, v8
	v_cvt_pk_bf16_f32 v5, v9, v10
	v_pk_mul_f32 v[28:29], v[28:29], v[0:1] op_sel_hi:[1,0]
	v_pk_mul_f32 v[26:27], v[26:27], v[0:1] op_sel_hi:[1,0]
	v_pk_mul_f32 v[24:25], v[24:25], v[0:1] op_sel_hi:[1,0]
	v_pk_mul_f32 v[22:23], v[22:23], v[0:1] op_sel_hi:[1,0]
	v_pk_mul_f32 v[20:21], v[20:21], v[0:1] op_sel_hi:[1,0]
	v_pk_mul_f32 v[18:19], v[18:19], v[0:1] op_sel_hi:[1,0]
	v_pk_mul_f32 v[16:17], v[16:17], v[0:1] op_sel_hi:[1,0]
	v_exp_f32_e32 v48, v48
	v_add_f32_e32 v49, v12, v49
	v_sub_f32_e32 v50, v62, v6
	v_mfma_f32_32x32x16_bf16 v[32:47], v[164:167], v[2:5], v[32:47]
	v_add_f32_e32 v49, v13, v49
	v_exp_f32_e32 v7, v50
	v_add_f32_e32 v49, v14, v49
	v_add_f32_e32 v49, v15, v49
	v_add_f32_e32 v49, v48, v49
	v_mfma_f32_32x32x16_bf16 v[16:31], v[168:171], v[2:5], v[16:31]
	v_sub_f32_e32 v2, v63, v6
	v_exp_f32_e32 v6, v2
	v_cvt_pk_bf16_f32 v2, v11, v12
	v_cvt_pk_bf16_f32 v3, v13, v14
	v_cvt_pk_bf16_f32 v4, v15, v48
	v_cvt_pk_bf16_f32 v5, v7, v6
	v_add_f32_e32 v7, v7, v49
	v_add_f32_e32 v6, v6, v7
	v_fmac_f32_e32 v6, v96, v0
	ds_bpermute_b32 v0, v103, v6
	v_mfma_f32_32x32x16_bf16 v[32:47], v[64:67], v[2:5], v[32:47]
	s_waitcnt lgkmcnt(0)
	v_add_f32_e32 v0, v6, v0
	v_mfma_f32_32x32x16_bf16 v[16:31], v[92:95], v[2:5], v[16:31]
	v_div_scale_f32 v2, s[2:3], v0, v0, 1.0
	v_rcp_f32_e32 v3, v2
	v_readlane_b32 s2, v253, 6
	v_readlane_b32 s3, v253, 7
	v_fma_f32 v4, -v2, v3, 1.0
	v_fmac_f32_e32 v3, v4, v3
	v_div_scale_f32 v4, vcc, 1.0, v0, 1.0
	v_mul_f32_e32 v5, v4, v3
	v_fma_f32 v6, -v2, v5, v4
	v_fmac_f32_e32 v5, v6, v3
	v_fma_f32 v2, -v2, v5, v4
	v_div_fmas_f32 v2, v2, v3, v5
	v_div_fixup_f32 v0, v2, v0, 1.0
	v_lshl_add_u64 v[2:3], s[6:7], 0, v[108:109]
	v_lshlrev_b64 v[2:3], 10, v[2:3]
	v_lshl_add_u64 v[2:3], s[2:3], 0, v[2:3]
	s_lshl_b32 s2, s12, 1
	s_mov_b32 s3, s4
	v_lshl_add_u64 v[2:3], v[2:3], 0, s[2:3]
	v_pk_mul_f32 v[4:5], v[32:33], v[0:1] op_sel_hi:[1,0]
	v_pk_mul_f32 v[6:7], v[34:35], v[0:1] op_sel_hi:[1,0]
	v_lshl_add_u64 v[2:3], v[2:3], 0, v[120:121]
	v_cvt_pk_bf16_f32 v4, v4, v5
	v_cvt_pk_bf16_f32 v5, v6, v7
	global_store_dwordx2 v[2:3], v[4:5], off
	v_pk_mul_f32 v[4:5], v[16:17], v[0:1] op_sel_hi:[1,0]
	v_pk_mul_f32 v[6:7], v[18:19], v[0:1] op_sel_hi:[1,0]
	v_cvt_pk_bf16_f32 v4, v4, v5
	v_cvt_pk_bf16_f32 v5, v6, v7
	global_store_dwordx2 v[2:3], v[4:5], off offset:64
	v_pk_mul_f32 v[4:5], v[36:37], v[0:1] op_sel_hi:[1,0]
	v_pk_mul_f32 v[6:7], v[38:39], v[0:1] op_sel_hi:[1,0]
	v_cvt_pk_bf16_f32 v4, v4, v5
	v_cvt_pk_bf16_f32 v5, v6, v7
	global_store_dwordx2 v[2:3], v[4:5], off offset:16
	v_pk_mul_f32 v[4:5], v[20:21], v[0:1] op_sel_hi:[1,0]
	v_pk_mul_f32 v[6:7], v[22:23], v[0:1] op_sel_hi:[1,0]
	v_cvt_pk_bf16_f32 v4, v4, v5
	v_cvt_pk_bf16_f32 v5, v6, v7
	global_store_dwordx2 v[2:3], v[4:5], off offset:80
	v_pk_mul_f32 v[4:5], v[40:41], v[0:1] op_sel_hi:[1,0]
	v_pk_mul_f32 v[6:7], v[42:43], v[0:1] op_sel_hi:[1,0]
	v_cvt_pk_bf16_f32 v4, v4, v5
	v_cvt_pk_bf16_f32 v5, v6, v7
	global_store_dwordx2 v[2:3], v[4:5], off offset:32
	v_pk_mul_f32 v[4:5], v[24:25], v[0:1] op_sel_hi:[1,0]
	v_pk_mul_f32 v[6:7], v[26:27], v[0:1] op_sel_hi:[1,0]
	v_cvt_pk_bf16_f32 v4, v4, v5
	v_cvt_pk_bf16_f32 v5, v6, v7
	global_store_dwordx2 v[2:3], v[4:5], off offset:96
	v_pk_mul_f32 v[4:5], v[44:45], v[0:1] op_sel_hi:[1,0]
	v_pk_mul_f32 v[6:7], v[46:47], v[0:1] op_sel_hi:[1,0]
	v_cvt_pk_bf16_f32 v4, v4, v5
	v_cvt_pk_bf16_f32 v5, v6, v7
	global_store_dwordx2 v[2:3], v[4:5], off offset:48
	v_pk_mul_f32 v[4:5], v[28:29], v[0:1] op_sel_hi:[1,0]
	v_pk_mul_f32 v[6:7], v[30:31], v[0:1] op_sel_hi:[1,0]
	v_cvt_pk_bf16_f32 v4, v4, v5
	v_cvt_pk_bf16_f32 v5, v6, v7
	s_cmpk_gt_i32 s5, 0xff
	global_store_dwordx2 v[2:3], v[4:5], off offset:112
	s_cbranch_scc0 .LBB0_384
